# re-entrant prologue-item loop: index-key pages + window-state copy moved from P0 into P3 tail slack (WG>=8)
# speedup vs baseline: 1.0174x; 1.0109x over previous
_Z6mk_fwd4Args:
	s_mov_b32 s100, s2
	s_mov_b32 s99, 0
	s_load_dwordx8 s[48:55], s[0:1], 0xc0
	v_writelane_b32 v254, s0, 0
	v_cmp_gt_u32_e32 vcc, 64, v0
	s_nop 0
	v_writelane_b32 v254, s1, 1
	s_load_dwordx2 s[0:1], s[0:1], 0xe0
	s_waitcnt lgkmcnt(0)
	v_writelane_b32 v254, s0, 2
	s_nop 1
	v_writelane_b32 v254, s1, 3
	s_and_saveexec_b64 s[4:5], vcc
	v_lshl_add_u32 v1, v0, 2, 0
	v_add_u32_e32 v1, 0x23f00, v1
	v_mov_b32_e32 v2, 0
	ds_write_b32 v1, v2
	s_or_b64 exec, exec, s[4:5]
	v_readlane_b32 s0, v254, 0
	v_readlane_b32 s1, v254, 1
	s_load_dwordx16 s[76:91], s[0:1], 0x0
	s_load_dwordx16 s[4:19], s[0:1], 0x40
	v_cmp_eq_u32_e32 vcc, 0, v0
	s_waitcnt lgkmcnt(0)
	s_barrier
	v_writelane_b32 v254, s4, 4
	s_nop 1
	v_writelane_b32 v254, s5, 5
	v_writelane_b32 v254, s6, 6
	v_writelane_b32 v254, s7, 7
	v_writelane_b32 v254, s8, 8
	v_writelane_b32 v254, s9, 9
	v_writelane_b32 v254, s10, 10
	v_writelane_b32 v254, s11, 11
	v_writelane_b32 v254, s12, 12
	v_writelane_b32 v254, s13, 13
	v_writelane_b32 v254, s14, 14
	v_writelane_b32 v254, s15, 15
	v_writelane_b32 v254, s16, 16
	v_writelane_b32 v254, s17, 17
	v_writelane_b32 v254, s18, 18
	v_writelane_b32 v254, s19, 19
	s_load_dwordx16 s[4:19], s[0:1], 0x80
	s_add_u32 s0, s54, 0x4000
	s_addc_u32 s1, s55, 0
	s_waitcnt lgkmcnt(0)
	v_writelane_b32 v254, s4, 20
	s_nop 1
	v_writelane_b32 v254, s5, 21
	v_writelane_b32 v254, s6, 22
	v_writelane_b32 v254, s7, 23
	v_writelane_b32 v254, s8, 24
	v_writelane_b32 v254, s9, 25
	v_writelane_b32 v254, s10, 26
	v_writelane_b32 v254, s11, 27
	v_writelane_b32 v254, s12, 28
	v_writelane_b32 v254, s13, 29
	v_writelane_b32 v254, s14, 30
	v_writelane_b32 v254, s15, 31
	v_writelane_b32 v254, s16, 32
	v_writelane_b32 v254, s17, 33
	v_writelane_b32 v254, s18, 34
	v_writelane_b32 v254, s19, 35
	v_writelane_b32 v254, s0, 36
	s_nop 1
	v_writelane_b32 v254, s1, 37
	s_nop 0
	v_readlane_b32 s0, v254, 2
	v_readlane_b32 s1, v254, 3
	s_sub_i32 s0, s1, s0
	s_mov_b32 s1, 0
	v_writelane_b32 v254, s1, 38
	s_cmp_lt_i32 s0, 2
	s_mov_b32 s0, 0
	v_writelane_b32 v254, s0, 39
	s_cbranch_scc1 .LBB0_7
	s_getreg_b32 s0, hwreg(HW_REG_XCC_ID, 0, 4)
	s_and_b32 s0, s0, 15
	v_writelane_b32 v254, s0, 39
	s_and_saveexec_b64 s[4:5], vcc
	s_cbranch_execz .LBB0_6
	s_mov_b64 s[6:7], exec
	v_mbcnt_lo_u32_b32 v1, s6, 0
	v_mbcnt_hi_u32_b32 v1, s7, v1
	v_cmp_eq_u32_e32 vcc, 0, v1
	s_and_b64 s[8:9], exec, vcc
	s_mov_b64 exec, s[8:9]
	s_cbranch_execz .LBB0_6
	v_readlane_b32 s0, v254, 39
	s_lshl_b32 s0, s0, 8
	s_bcnt1_i32_b64 s1, s[6:7]
	v_mov_b32_e32 v1, s0
	v_mov_b32_e32 v2, s1
	v_readlane_b32 s0, v254, 36
	v_readlane_b32 s1, v254, 37
	s_nop 4
	global_atomic_add v1, v2, s[0:1] offset:1024

.LBB0_7:
	s_nop 0
	v_readlane_b32 s0, v254, 2
	v_readlane_b32 s1, v254, 3
	v_writelane_b32 v254, s48, 40
	s_cmp_lt_i32 s0, 1
	s_cselect_b64 s[4:5], -1, 0
	v_writelane_b32 v254, s49, 41
	v_writelane_b32 v254, s50, 42
	s_cmp_gt_i32 s1, 0
	v_writelane_b32 v254, s51, 43
	s_cselect_b64 s[6:7], -1, 0
	v_writelane_b32 v254, s52, 44
	s_and_b64 s[6:7], s[4:5], s[6:7]
	v_writelane_b32 v254, s53, 45
	s_andn2_b64 vcc, exec, s[6:7]
	v_and_b32_e32 v206, 63, v0
	v_writelane_b32 v254, s54, 46
	v_writelane_b32 v254, s55, 47
	s_cbranch_vccnz .LBB0_113
	s_movk_i32 s98, 0x2a7f
	v_readlane_b32 s0, v254, 0
	v_readlane_b32 s1, v254, 1
	s_load_dword s8, s[0:1], 0xe8
	v_readfirstlane_b32 s0, v0
	s_lshr_b32 s9, s0, 6
	s_lshl_b32 s0, s2, 3
	s_add_i32 s10, s9, s0
	s_waitcnt lgkmcnt(0)
	s_lshl_b32 s3, s8, 3
	s_cmpk_gt_i32 s10, 0x267f
	v_and_b32_e32 v34, 63, v0
	s_cbranch_scc1 .LBB0_78
	s_mov_b64 exec, -1
	v_readlane_b32 s0, v254, 0
	v_readlane_b32 s1, v254, 1
	s_nop 4
	s_load_dwordx2 s[56:57], s[0:1], 0x50
	s_load_dwordx2 s[58:59], s[0:1], 0x98
	s_load_dwordx2 s[60:61], s[0:1], 0x60
	s_load_dwordx2 s[62:63], s[0:1], 0xd8
	s_load_dwordx2 s[64:65], s[0:1], 0x48
	v_readfirstlane_b32 s4, v0
	v_and_b32_e32 v7, 63, v0
	s_lshr_b32 s4, s4, 6
	v_lshrrev_b32_e32 v1, 3, v7
	v_and_b32_e32 v2, 7, v7
	s_lshl_b32 s5, s4, 14
	v_lshlrev_b32_e32 v5, 5, v2
	s_movk_i32 s18, 0x420
	v_mul_u32_u24_e32 v4, s18, v2
	v_lshlrev_b32_e32 v2, 4, v2
	s_movk_i32 s18, 0x84
	v_mad_u32_u24 v3, v1, s18, v2
	v_lshl_add_u32 v4, v1, 2, v4
	v_add_u32_e32 v3, s5, v3
	v_add_u32_e32 v4, s5, v4
	v_mov_b32_e32 v148, v3
	v_add_u32_e32 v149, 1056, v3
	v_add_u32_e32 v150, 2112, v3
	v_add_u32_e32 v151, 3168, v3
	v_add_u32_e32 v152, 4224, v3
	v_add_u32_e32 v153, 5280, v3
	v_add_u32_e32 v154, 6336, v3
	v_add_u32_e32 v155, 7392, v3
	s_waitcnt lgkmcnt(0)
	s_mov_b32 s20, s10
	s_mov_b32 s21, s3
	s_cmp_ge_u32 s20, 0x2680
	s_cbranch_scc1 .LBB0_78
	s_mov_b32 s26, s20
	s_cmp_lt_u32 s26, 0x2080
	s_cbranch_scc1 .Ltrp0_i1_s0
	s_sub_u32 s26, s26, 0x2080
	s_cmp_lt_u32 s26, 0x400
	s_cbranch_scc1 .Ltrp0_i1_s1
	s_sub_u32 s26, s26, 0x400
	s_cmp_lt_u32 s26, 0x100
	s_cbranch_scc1 .Ltrp0_i1_s2
	s_sub_u32 s26, s26, 0x100
	s_branch .Ltrp0_i1_s3

.LBB0_78:
	s_cmp_gt_i32 s10, s98
	s_cbranch_scc1 .LBB0_109
	s_waitcnt vmcnt(8)
	v_mov_b32_e32 v27, 0
	v_lshlrev_b32_e32 v26, 4, v34
	v_readlane_b32 s16, v254, 4
	v_lshl_add_u64 v[2:3], s[52:53], 0, v[26:27]
	s_mov_b64 s[4:5], 0x5240000
	v_readlane_b32 s18, v254, 6
	v_readlane_b32 s19, v254, 7
	s_waitcnt vmcnt(6)
	v_lshl_add_u64 v[28:29], s[82:83], 0, v[26:27]
	s_waitcnt vmcnt(4)
	v_lshl_add_u64 v[30:31], s[80:81], 0, v[26:27]
	v_lshl_add_u64 v[32:33], v[2:3], 0, s[4:5]
	v_lshl_add_u64 v[36:37], s[18:19], 0, v[26:27]
	s_mov_b64 s[4:5], 0x4000
	v_lshlrev_b32_e32 v26, 3, v34
	v_lshl_add_u64 v[38:39], v[36:37], 0, s[4:5]
	v_lshl_add_u64 v[2:3], s[54:55], 0, v[26:27]
	s_mov_b64 s[4:5], 0x9f00000
	v_lshl_add_u64 v[40:41], v[2:3], 0, s[4:5]
	s_mov_b64 s[4:5], 0x5000
	v_lshl_add_u64 v[42:43], v[36:37], 0, s[4:5]
	s_mov_b64 s[4:5], 0x5400
	v_lshl_add_u64 v[44:45], v[36:37], 0, s[4:5]
	s_mov_b64 s[4:5], 0x5800
	v_lshl_add_u64 v[46:47], v[36:37], 0, s[4:5]
	s_mov_b64 s[4:5], 0x5c00
	v_lshl_add_u64 v[48:49], v[36:37], 0, s[4:5]
	s_mov_b64 s[4:5], 0x7e00000
	s_add_u32 s12, s54, 0x2c39a000
	v_lshl_add_u64 v[50:51], v[2:3], 0, s[4:5]
	v_bfe_u32 v2, v0, 4, 2
	s_addc_u32 s13, s55, 0
	v_readlane_b32 s20, v254, 8
	v_readlane_b32 s24, v254, 12
	v_mul_hi_u32_u24_e32 v3, 0x500, v2
	v_mul_u32_u24_e32 v2, 0x500, v2
	v_and_b32_e32 v6, 15, v0
	v_lshrrev_b32_e32 v4, 4, v34
	v_lshlrev_b32_e32 v5, 3, v0
	v_readlane_b32 s21, v254, 9
	v_readlane_b32 s25, v254, 13
	s_add_u32 s20, s24, 0x7c00
	v_lshl_or_b32 v2, v6, 4, v2
	v_readlane_b32 s23, v254, 11
	s_mov_b64 s[4:5], 0x1000
	s_addc_u32 s21, s25, 0
	s_lshl_b32 s0, s2, 5
	s_lshl_b32 s1, s9, 2
	v_lshl_add_u64 v[60:61], s[86:87], 0, v[2:3]
	v_and_or_b32 v2, v5, 48, v4
	v_and_b32_e32 v4, 1, v0
	v_lshl_add_u64 v[52:53], v[36:37], 0, s[4:5]
	s_mov_b64 s[4:5], 0x1400
	s_add_i32 s23, s0, s1
	v_lshlrev_b32_e32 v3, 7, v34
	v_lshlrev_b32_e32 v4, 3, v4
	s_movk_i32 s0, 0x400
	v_readlane_b32 s26, v254, 14
	v_lshl_add_u64 v[54:55], v[36:37], 0, s[4:5]
	s_mov_b64 s[4:5], 0x1800
	v_lshlrev_b32_e32 v2, 4, v2
	v_and_or_b32 v26, v3, s0, v4
	s_lshl_b32 s0, s2, 6
	s_lshl_b32 s1, s9, 3
	v_lshl_add_u64 v[56:57], v[36:37], 0, s[4:5]
	s_mov_b64 s[4:5], 0x1c00
	v_or_b32_e32 v62, 0xc0, v2
	v_lshl_add_u64 v[64:65], s[54:55], 0, v[26:27]
	s_add_i32 s26, s0, s1
	v_or_b32_e32 v66, 0x80, v2
	v_or_b32_e32 v68, 64, v2
	v_lshlrev_b32_e32 v2, 7, v0
	s_movk_i32 s0, 0x330
	v_lshlrev_b32_e32 v26, 3, v6
	v_readlane_b32 s22, v254, 10
	v_readlane_b32 s27, v254, 15
	v_readlane_b32 s28, v254, 16
	v_readlane_b32 s29, v254, 17
	v_readlane_b32 s30, v254, 18
	v_readlane_b32 s31, v254, 19
	v_lshl_add_u64 v[58:59], v[36:37], 0, s[4:5]
	v_bitop3_b32 v70, v2, s0, v34 bitop3:0xc8
	v_lshl_add_u64 v[2:3], s[54:55], 0, v[26:27]
	s_mov_b64 s[4:5], 0x24398400
	s_lshl_b32 s0, s2, 16
	s_lshl_b32 s1, s9, 13
	v_bfe_u32 v1, v0, 4, 1
	s_add_i32 s22, s10, 0xffffcd80
	s_lshl_b32 s24, s8, 5
	v_mov_b32_e32 v63, v27
	s_add_i32 s25, s10, 0xffffd580
	s_lshl_b32 s27, s8, 6
	v_mov_b32_e32 v67, v27
	v_mov_b32_e32 v69, v27
	v_mov_b32_e32 v71, v27
	v_lshl_add_u64 v[72:73], v[2:3], 0, s[4:5]
	s_add_i32 s28, s10, 0xffffdd80
	s_add_i32 s9, s0, s1
	s_lshl_b32 s29, s8, 16
	s_mov_b32 s15, 0
	s_movk_i32 s30, 0x1000
	s_mov_b32 s31, 0x5122a000
	s_movk_i32 s34, 0x2000
	s_movk_i32 s35, 0x4000
	s_movk_i32 s36, 0x5000
	s_mov_b32 s37, 0x5122b000
	s_movk_i32 s38, 0x6000
	s_movk_i32 s39, 0x7000
	s_mov_b32 s44, 0x5122c000
	v_mov_b32_e32 v35, 0x358637bd
	s_mov_b32 s45, 0x800000
	v_lshlrev_b32_e32 v26, 4, v34
	s_mov_b32 s56, s10
	v_readlane_b32 s17, v254, 5
	s_branch .LBB0_82

.LBB0_81:
	s_add_i32 s10, s10, s3
	s_add_i32 s22, s22, s3
	s_sub_i32 s56, s56, s3
	s_add_i32 s23, s23, s24
	s_add_i32 s25, s25, s3
	s_add_i32 s26, s26, s27
	s_add_i32 s28, s28, s3
	s_add_i32 s9, s9, s29
	s_cmp_le_i32 s10, s98
	s_cbranch_scc0 .LBB0_109

.LBB0_112:
	s_or_b64 exec, exec, s[4:5]
	s_cmp_eq_u32 s99, 0
	s_cbranch_scc1 .Lrc_p0b
	s_cmp_eq_u32 s99, 2
	s_cbranch_scc1 .Lrc_p0done
	s_cmp_eq_u32 s99, 3
	s_cbranch_scc1 .Lrc_c2
	s_cmp_eq_u32 s99, 7
	s_cbranch_scc1 .Lrc_p1ret
	s_cmp_eq_u32 s99, 4
	s_cbranch_scc0 .LBB0_113
	s_mov_b32 s2, s100
	s_mov_b32 s99, 6
	s_branch .LBB0_949
.Lrc_p0b:
	s_mov_b32 s99, 2
	s_add_u32 s2, s100, 0x650
	s_movk_i32 s98, 0x32ff
	v_readlane_b32 s0, v254, 0
	v_readlane_b32 s1, v254, 1
	s_nop 4
	s_load_dword s8, s[0:1], 0xe8
	s_waitcnt lgkmcnt(0)
	v_readfirstlane_b32 s9, v0
	s_lshr_b32 s9, s9, 6
	s_lshl_b32 s10, s2, 3
	s_add_u32 s10, s10, s9
	s_lshl_b32 s3, s8, 3
	v_and_b32_e32 v34, 63, v0
	s_branch .LBB0_78
.Lrc_c2:
	s_mov_b32 s99, 4
	s_sub_u32 s2, s100, 8
	s_add_u32 s2, s2, 0x660
	s_movk_i32 s98, 0x727f
	v_readlane_b32 s0, v254, 0
	v_readlane_b32 s1, v254, 1
	s_nop 4
	s_load_dword s8, s[0:1], 0xe8
	s_waitcnt lgkmcnt(0)
	s_sub_u32 s8, s8, 8
	v_readfirstlane_b32 s9, v0
	s_lshr_b32 s9, s9, 6
	s_lshl_b32 s10, s2, 3
	s_add_u32 s10, s10, s9
	s_lshl_b32 s3, s8, 3
	v_and_b32_e32 v34, 63, v0
	s_branch .LBB0_78
.Lrc_p1ret:
	s_mov_b32 s2, s100
	s_mov_b32 s99, 5
	v_readlane_b32 s48, v254, 40
	v_readlane_b32 s49, v254, 41
	v_readlane_b32 s50, v254, 42
	v_readlane_b32 s51, v254, 43
	v_readlane_b32 s52, v254, 44
	v_readlane_b32 s53, v254, 45
	v_readlane_b32 s54, v254, 46
	v_readlane_b32 s55, v254, 47
	s_nop 4
	s_branch .Lrc_p1skip
.Lrc_p0done:
	s_mov_b32 s2, s100
	s_mov_b32 s99, 5

.LBB0_325:
.Lrc_p1skip:
	v_readlane_b32 s0, v254, 2
	v_readlane_b32 s1, v254, 3
	s_cmp_gt_i32 s1, 2
	s_cselect_b64 s[4:5], -1, 0
	s_and_b64 s[6:7], s[6:7], s[4:5]
	s_andn2_b64 vcc, exec, s[6:7]
	s_cbranch_vccnz .LBB0_375
	s_waitcnt vmcnt(0) lgkmcnt(0)
	s_barrier
	v_readfirstlane_b32 s0, v0
	s_lshr_b32 s0, s0, 6
	s_cmp_lg_u32 s0, 0
	s_cbranch_scc1 .Lgb1_close
	s_mov_b64 s[10:11], exec
	s_mov_b64 exec, 1
	v_readlane_b32 s12, v254, 36
	v_readlane_b32 s13, v254, 37
	v_readlane_b32 s14, v254, 38
	v_readlane_b32 s15, v254, 39
	s_nop 1
	v_mov_b32_e32 v1, s14
	ds_read_b32 v2, v1
	ds_read_b32 v3, v1 offset:4
	ds_read_b32 v4, v1 offset:8
	s_waitcnt lgkmcnt(0)
	v_readfirstlane_b32 s16, v2
	v_readfirstlane_b32 s17, v3
	v_readfirstlane_b32 s18, v4
	s_cmp_lg_u32 s16, 0
	s_cbranch_scc1 .Lgb1_have
	v_readlane_b32 s0, v254, 0
	v_readlane_b32 s1, v254, 1
	s_nop 4
	s_load_dwordx2 s[20:21], s[0:1], 0xe8
	s_load_dword s22, s[0:1], 0xf0
	v_mov_b32_e32 v5, 0
	v_mov_b32_e32 v6, 0x1000
	s_mov_b32 s19, 0
	s_waitcnt lgkmcnt(0)
	s_mul_i32 s20, s20, s21
	s_mul_i32 s20, s20, s22

.Lrc_p3call:
	s_cmp_eq_u32 s99, 5
	s_cbranch_scc0 .LBB0_949
	s_mov_b32 s99, 3
	s_mov_b64 exec, -1
	v_readlane_b32 s0, v254, 0
	v_readlane_b32 s1, v254, 1
	v_readlane_b32 s52, v254, 44
	v_readlane_b32 s53, v254, 45
	v_readlane_b32 s54, v254, 46
	v_readlane_b32 s55, v254, 47
	s_nop 4
	s_load_dwordx16 s[76:91], s[0:1], 0x0
	s_load_dword s8, s[0:1], 0xe8
	s_waitcnt lgkmcnt(0)
	s_sub_u32 s8, s8, 8
	s_sub_u32 s2, s100, 8
	s_add_u32 s2, s2, 0x550
	s_movk_i32 s98, 0x327f
	v_readfirstlane_b32 s9, v0
	s_lshr_b32 s9, s9, 6
	s_lshl_b32 s10, s2, 3
	s_add_u32 s10, s10, s9
	s_lshl_b32 s3, s8, 3
	v_and_b32_e32 v34, 63, v0
	s_branch .LBB0_78

	.amdhsa_kernel _Z6mk_fwd4Args
		.amdhsa_group_segment_fixed_size 0
		.amdhsa_private_segment_fixed_size 0
		.amdhsa_kernarg_size 488
		.amdhsa_user_sgpr_count 2
		.amdhsa_user_sgpr_dispatch_ptr 0
		.amdhsa_user_sgpr_queue_ptr 0
		.amdhsa_user_sgpr_kernarg_segment_ptr 1
		.amdhsa_user_sgpr_dispatch_id 0
		.amdhsa_user_sgpr_kernarg_preload_length 0
		.amdhsa_user_sgpr_kernarg_preload_offset 0
		.amdhsa_user_sgpr_private_segment_size 0
		.amdhsa_uses_dynamic_stack 0
		.amdhsa_enable_private_segment 0
		.amdhsa_system_sgpr_workgroup_id_x 1
		.amdhsa_system_sgpr_workgroup_id_y 0
		.amdhsa_system_sgpr_workgroup_id_z 0
		.amdhsa_system_sgpr_workgroup_info 0
		.amdhsa_system_vgpr_workitem_id 0
		.amdhsa_next_free_vgpr 255
		.amdhsa_next_free_sgpr 102
		.amdhsa_accum_offset 256
		.amdhsa_reserve_vcc 1
		.amdhsa_float_round_mode_32 0
		.amdhsa_float_round_mode_16_64 0
		.amdhsa_float_denorm_mode_32 3
		.amdhsa_float_denorm_mode_16_64 3
		.amdhsa_dx10_clamp 1
		.amdhsa_ieee_mode 1
		.amdhsa_fp16_overflow 0
		.amdhsa_tg_split 0
		.amdhsa_exception_fp_ieee_invalid_op 0
		.amdhsa_exception_fp_denorm_src 0
		.amdhsa_exception_fp_ieee_div_zero 0
		.amdhsa_exception_fp_ieee_overflow 0
		.amdhsa_exception_fp_ieee_underflow 0
		.amdhsa_exception_fp_ieee_inexact 0
		.amdhsa_exception_int_div_zero 0
	.end_amdhsa_kernel

amdhsa.kernels:
  - .agpr_count:     0
    .args:
      - .offset:         0
        .size:           232
        .value_kind:     by_value
      - .offset:         232
        .size:           4
        .value_kind:     hidden_block_count_x
      - .offset:         236
        .size:           4
        .value_kind:     hidden_block_count_y
      - .offset:         240
        .size:           4
        .value_kind:     hidden_block_count_z
      - .offset:         244
        .size:           2
        .value_kind:     hidden_group_size_x
      - .offset:         246
        .size:           2
        .value_kind:     hidden_group_size_y
      - .offset:         248
        .size:           2
        .value_kind:     hidden_group_size_z
      - .offset:         250
        .size:           2
        .value_kind:     hidden_remainder_x
      - .offset:         252
        .size:           2
        .value_kind:     hidden_remainder_y
      - .offset:         254
        .size:           2
        .value_kind:     hidden_remainder_z
      - .offset:         272
        .size:           8
        .value_kind:     hidden_global_offset_x
      - .offset:         280
        .size:           8
        .value_kind:     hidden_global_offset_y
      - .offset:         288
        .size:           8
        .value_kind:     hidden_global_offset_z
      - .offset:         296
        .size:           2
        .value_kind:     hidden_grid_dims
      - .offset:         352
        .size:           4
        .value_kind:     hidden_dynamic_lds_size
    .group_segment_fixed_size: 0
    .kernarg_segment_align: 8
    .kernarg_segment_size: 488
    .language:       OpenCL C
    .language_version:
      - 2
      - 0
    .max_flat_workgroup_size: 512
    .name:           _Z6mk_fwd4Args
    .private_segment_fixed_size: 0
    .sgpr_count:     108
    .sgpr_spill_count: 66
    .symbol:         _Z6mk_fwd4Args.kd
    .uniform_work_group_size: 1
    .uses_dynamic_stack: false
    .vgpr_count:     255
    .vgpr_spill_count: 0
    .wavefront_size: 64
